# P0 remainder rows de-serialized (all loads up front) + pipelined main loop, on top of v15 (counted vmcnt in convert loops, GEMM slot-edge trims)
# speedup vs baseline: 1.0058x; 1.0058x over previous
.LBB0_27:
	v_lshl_add_u64 v[116:117], v[20:21], 0, s[10:11]
	v_cmp_eq_u32_e64 s[0:1], 4, v3
	v_lshl_add_u64 v[120:121], v[116:117], 0, s[10:11]
	v_lshl_add_u64 v[132:133], v[120:121], 0, s[10:11]
	s_nop 1
	v_cndmask_b32_e64 v132, v120, v132, s[0:1]
	v_cndmask_b32_e64 v133, v121, v133, s[0:1]
	global_load_dwordx4 v[28:31], v[20:21], off nt
	s_nop 0
	global_load_dwordx4 v[116:119], v[116:117], off nt
	s_nop 0
	global_load_dwordx4 v[120:123], v[120:121], off nt
	s_nop 0
	global_load_dwordx4 v[132:135], v[132:133], off nt
	ds_read_b128 v[40:43], v23
	ds_read_b128 v[124:127], v23 offset:336
	ds_read_b128 v[128:131], v23 offset:672
	ds_read_b128 v[136:139], v23 offset:1008
	v_mad_u32_u24 v22, v3, 21, v22
	s_waitcnt lgkmcnt(0)
	v_mov_b32_e32 v44, v43
	s_waitcnt vmcnt(3)
	v_pk_fma_f32 v[18:19], v[30:31], v[40:41], v[18:19] op_sel_hi:[1,0,1]
	v_pk_fma_f32 v[16:17], v[28:29], v[40:41], v[16:17] op_sel_hi:[1,0,1]
	v_pk_fma_f32 v[14:15], v[30:31], v[40:41], v[14:15] op_sel:[0,1,0]
	v_pk_fma_f32 v[12:13], v[28:29], v[40:41], v[12:13] op_sel:[0,1,0]
	v_pk_fma_f32 v[10:11], v[30:31], v[42:43], v[10:11] op_sel_hi:[1,0,1]
	v_pk_fma_f32 v[8:9], v[28:29], v[42:43], v[8:9] op_sel_hi:[1,0,1]
	v_pk_fma_f32 v[6:7], v[30:31], v[44:45], v[6:7] op_sel_hi:[1,0,1]
	v_pk_fma_f32 v[4:5], v[28:29], v[44:45], v[4:5] op_sel_hi:[1,0,1]
	v_mov_b32_e32 v44, v127
	s_waitcnt vmcnt(2)
	v_pk_fma_f32 v[18:19], v[118:119], v[124:125], v[18:19] op_sel_hi:[1,0,1]
	v_pk_fma_f32 v[16:17], v[116:117], v[124:125], v[16:17] op_sel_hi:[1,0,1]
	v_pk_fma_f32 v[14:15], v[118:119], v[124:125], v[14:15] op_sel:[0,1,0]
	v_pk_fma_f32 v[12:13], v[116:117], v[124:125], v[12:13] op_sel:[0,1,0]
	v_pk_fma_f32 v[10:11], v[118:119], v[126:127], v[10:11] op_sel_hi:[1,0,1]
	v_pk_fma_f32 v[8:9], v[116:117], v[126:127], v[8:9] op_sel_hi:[1,0,1]
	v_pk_fma_f32 v[6:7], v[118:119], v[44:45], v[6:7] op_sel_hi:[1,0,1]
	v_pk_fma_f32 v[4:5], v[116:117], v[44:45], v[4:5] op_sel_hi:[1,0,1]
	v_mov_b32_e32 v44, v131
	s_waitcnt vmcnt(1)
	v_pk_fma_f32 v[18:19], v[122:123], v[128:129], v[18:19] op_sel_hi:[1,0,1]
	v_pk_fma_f32 v[16:17], v[120:121], v[128:129], v[16:17] op_sel_hi:[1,0,1]
	v_pk_fma_f32 v[14:15], v[122:123], v[128:129], v[14:15] op_sel:[0,1,0]
	v_pk_fma_f32 v[12:13], v[120:121], v[128:129], v[12:13] op_sel:[0,1,0]
	v_pk_fma_f32 v[10:11], v[122:123], v[130:131], v[10:11] op_sel_hi:[1,0,1]
	v_pk_fma_f32 v[8:9], v[120:121], v[130:131], v[8:9] op_sel_hi:[1,0,1]
	v_pk_fma_f32 v[6:7], v[122:123], v[44:45], v[6:7] op_sel_hi:[1,0,1]
	v_pk_fma_f32 v[4:5], v[120:121], v[44:45], v[4:5] op_sel_hi:[1,0,1]
	s_and_saveexec_b64 s[22:23], s[0:1]
	v_mov_b32_e32 v44, v139
	s_waitcnt vmcnt(0)
	v_pk_fma_f32 v[18:19], v[134:135], v[136:137], v[18:19] op_sel_hi:[1,0,1]
	v_pk_fma_f32 v[16:17], v[132:133], v[136:137], v[16:17] op_sel_hi:[1,0,1]
	v_pk_fma_f32 v[14:15], v[134:135], v[136:137], v[14:15] op_sel:[0,1,0]
	v_pk_fma_f32 v[12:13], v[132:133], v[136:137], v[12:13] op_sel:[0,1,0]
	v_pk_fma_f32 v[10:11], v[134:135], v[138:139], v[10:11] op_sel_hi:[1,0,1]
	v_pk_fma_f32 v[8:9], v[132:133], v[138:139], v[8:9] op_sel_hi:[1,0,1]
	v_pk_fma_f32 v[6:7], v[134:135], v[44:45], v[6:7] op_sel_hi:[1,0,1]
	v_pk_fma_f32 v[4:5], v[132:133], v[44:45], v[4:5] op_sel_hi:[1,0,1]
	s_or_b64 exec, exec, s[22:23]
	v_lshlrev_b32_e32 v20, 4, v22
